# PH8: workgroups with one unit fewer start their GEMM units ~18 us later (s_sleep), shifting their unit boundaries against the other half
# speedup vs baseline: 1.0009x; 1.0009x over previous
; __global__ void __launch_bounds__(NWAVES * 64, 2) hybrid_fwd(Args args) {
;     ...
;     if (IN(8)) {
;         {
;             const int rem = (32 * 44) % G; const bool light = rem == 0 || bx >= rem; const int nl = rem == 0 ? G : G - rem, il = rem == 0 ? bx : bx - rem;
;             if (light) for (int r = il * NWAVES + wave; r < conv_items(5632, 2048); r += nl * NWAVES) conv_item<J_WDOWN>(P, r, lane);
;             __syncthreads(); }
;         Sched<8> S(P, G, bx); Epi<8> E(P); pg8::gemm_run(lds, S, E);
.LBB0_990:
	s_cmpk_lt_u32 s2, 0x80
	s_cbranch_scc1 .Lprobe_skip
	s_sleep 127
	s_sleep 127
	s_sleep 127
	s_sleep 127
